# E16 + SwiGLU epilogue of both gate/up GEMMs regenerated with packed f32 ops (v_pk_mul_f32/v_pk_add_f32): 4 packed + 4 transcendental + 1 cvt per element pair instead of 8 scalar + 4 + 1, bit-identical
# baseline (speedup 1.0000x reference)
; __device__ __forceinline__ unsigned cvt_pk_bf16(float lo, float hi) { unsigned r; asm volatile("v_cvt_pk_bf16_f32 %0, %1, %2" : "=v"(r) : "v"(lo), "v"(hi)); return r; }
; __device__ __forceinline__ float silu_mul(float g, float u) { return g * u * __builtin_amdgcn_rcpf(1.0f + __builtin_amdgcn_exp2f(-1.4426950408889634f * g)); }
;     __device__ __forceinline__ void operator()(const f32x4 (&acc)[2][2][4][2], const Unit& u, int wr, int wc, int fr, int fq) const {
;         const int row0 = u.pm * BM + wr * 64 + fr, col0 = u.pn * HALF + wc * 32 + 8 * fq;
; #pragma unroll
;         for (int ai = 0; ai < 2; ++ai)
; #pragma unroll
;             for (int m = 0; m < 4; ++m) { bf16_t* rowp = O + (size_t)(row0 + ai * HALF + m * 16) * ldc + col0;
;                 const f32x4 g0 = acc[ai][0][m][0], g1 = acc[ai][0][m][1], u0 = acc[ai][1][m][0], u1 = acc[ai][1][m][1];
;                 u32x4 w; w.x = cvt_pk_bf16(silu_mul(g0[0], u0[0]), silu_mul(g0[1], u0[1])); w.y = cvt_pk_bf16(silu_mul(g0[2], u0[2]), silu_mul(g0[3], u0[3]));
;                 w.z = cvt_pk_bf16(silu_mul(g1[0], u1[0]), silu_mul(g1[1], u1[1])); w.w = cvt_pk_bf16(silu_mul(g1[2], u1[2]), silu_mul(g1[3], u1[3]));
;                 *(u32x4*)rowp = w; }
.LBB0_127:
	v_mov_b32_e32 v228, 0xbfb8aa3b
	v_mov_b32_e32 v229, 0xbfb8aa3b
	v_mov_b32_e32 v230, 1.0
	v_mov_b32_e32 v231, 1.0
	v_lshl_or_b32 v144, s44, 7, v150
	v_lshl_add_u32 v154, s18, 8, v148
	v_ashrrev_i32_e32 v145, 31, v144
	v_mov_b64_e32 v[146:147], s[4:5]
	v_lshlrev_b64 v[144:145], 1, v[144:145]
	v_mad_i64_i32 v[236:237], s[20:21], v154, s43, v[146:147]
	v_pk_mul_f32 v[240:241], v[124:125], v[228:229]
	v_pk_mul_f32 v[242:243], v[126:127], v[228:229]
	v_pk_mul_f32 v[244:245], v[116:117], v[228:229]
	v_pk_mul_f32 v[246:247], v[118:119], v[228:229]
	v_lshl_add_u64 v[236:237], v[236:237], 0, v[144:145]
	v_exp_f32_e32 v240, v240
	v_exp_f32_e32 v241, v241
	v_exp_f32_e32 v242, v242
	v_exp_f32_e32 v243, v243
	v_exp_f32_e32 v244, v244
	v_exp_f32_e32 v245, v245
	v_exp_f32_e32 v246, v246
	v_exp_f32_e32 v247, v247
	v_pk_mul_f32 v[120:121], v[124:125], v[120:121]
	v_pk_mul_f32 v[122:123], v[126:127], v[122:123]
	v_pk_mul_f32 v[112:113], v[116:117], v[112:113]
	v_pk_mul_f32 v[114:115], v[118:119], v[114:115]
	v_pk_add_f32 v[240:241], v[240:241], v[230:231]
	v_pk_add_f32 v[242:243], v[242:243], v[230:231]
	v_pk_add_f32 v[244:245], v[244:245], v[230:231]
	v_pk_add_f32 v[246:247], v[246:247], v[230:231]
	v_rcp_f32_e32 v240, v240
	v_rcp_f32_e32 v241, v241
	v_rcp_f32_e32 v242, v242
	v_rcp_f32_e32 v243, v243
	v_rcp_f32_e32 v244, v244
	v_rcp_f32_e32 v245, v245
	v_rcp_f32_e32 v246, v246
	v_rcp_f32_e32 v247, v247
	v_pk_mul_f32 v[120:121], v[120:121], v[240:241]
	v_pk_mul_f32 v[122:123], v[122:123], v[242:243]
	v_pk_mul_f32 v[112:113], v[112:113], v[244:245]
	v_pk_mul_f32 v[114:115], v[114:115], v[246:247]
	v_cvt_pk_bf16_f32 v232, v120, v121
	v_cvt_pk_bf16_f32 v233, v122, v123
	v_cvt_pk_bf16_f32 v234, v112, v113
	v_cvt_pk_bf16_f32 v235, v114, v115
	flat_store_dwordx4 v[236:237], v[232:235]
	v_or_b32_e32 v238, 16, v154
	v_mad_i64_i32 v[236:237], s[20:21], v238, s43, v[146:147]
	v_pk_mul_f32 v[240:241], v[108:109], v[228:229]
	v_pk_mul_f32 v[242:243], v[110:111], v[228:229]
	v_pk_mul_f32 v[244:245], v[100:101], v[228:229]
	v_pk_mul_f32 v[246:247], v[102:103], v[228:229]
	v_lshl_add_u64 v[236:237], v[236:237], 0, v[144:145]
	v_exp_f32_e32 v240, v240
	v_exp_f32_e32 v241, v241
	v_exp_f32_e32 v242, v242
	v_exp_f32_e32 v243, v243
	v_exp_f32_e32 v244, v244
	v_exp_f32_e32 v245, v245
	v_exp_f32_e32 v246, v246
	v_exp_f32_e32 v247, v247
	v_pk_mul_f32 v[104:105], v[108:109], v[104:105]
	v_pk_mul_f32 v[106:107], v[110:111], v[106:107]
	v_pk_mul_f32 v[96:97], v[100:101], v[96:97]
	v_pk_mul_f32 v[98:99], v[102:103], v[98:99]
	v_pk_add_f32 v[240:241], v[240:241], v[230:231]
	v_pk_add_f32 v[242:243], v[242:243], v[230:231]
	v_pk_add_f32 v[244:245], v[244:245], v[230:231]
	v_pk_add_f32 v[246:247], v[246:247], v[230:231]
	v_rcp_f32_e32 v240, v240
	v_rcp_f32_e32 v241, v241
	v_rcp_f32_e32 v242, v242
	v_rcp_f32_e32 v243, v243
	v_rcp_f32_e32 v244, v244
	v_rcp_f32_e32 v245, v245
	v_rcp_f32_e32 v246, v246
	v_rcp_f32_e32 v247, v247
	v_pk_mul_f32 v[104:105], v[104:105], v[240:241]
	v_pk_mul_f32 v[106:107], v[106:107], v[242:243]
	v_pk_mul_f32 v[96:97], v[96:97], v[244:245]
	v_pk_mul_f32 v[98:99], v[98:99], v[246:247]
	v_cvt_pk_bf16_f32 v232, v104, v105
	v_cvt_pk_bf16_f32 v233, v106, v107
	v_cvt_pk_bf16_f32 v234, v96, v97
	v_cvt_pk_bf16_f32 v235, v98, v99
	flat_store_dwordx4 v[236:237], v[232:235]
	v_or_b32_e32 v238, 32, v154
	v_mad_i64_i32 v[236:237], s[20:21], v238, s43, v[146:147]
	v_pk_mul_f32 v[240:241], v[92:93], v[228:229]
	v_pk_mul_f32 v[242:243], v[94:95], v[228:229]
	v_pk_mul_f32 v[244:245], v[84:85], v[228:229]
	v_pk_mul_f32 v[246:247], v[86:87], v[228:229]
	v_lshl_add_u64 v[236:237], v[236:237], 0, v[144:145]
	v_exp_f32_e32 v240, v240
	v_exp_f32_e32 v241, v241
	v_exp_f32_e32 v242, v242
	v_exp_f32_e32 v243, v243
	v_exp_f32_e32 v244, v244
	v_exp_f32_e32 v245, v245
	v_exp_f32_e32 v246, v246
	v_exp_f32_e32 v247, v247
	v_pk_mul_f32 v[88:89], v[92:93], v[88:89]
	v_pk_mul_f32 v[90:91], v[94:95], v[90:91]
	v_pk_mul_f32 v[80:81], v[84:85], v[80:81]
	v_pk_mul_f32 v[82:83], v[86:87], v[82:83]
	v_pk_add_f32 v[240:241], v[240:241], v[230:231]
	v_pk_add_f32 v[242:243], v[242:243], v[230:231]
	v_pk_add_f32 v[244:245], v[244:245], v[230:231]
	v_pk_add_f32 v[246:247], v[246:247], v[230:231]
	v_rcp_f32_e32 v240, v240
	v_rcp_f32_e32 v241, v241
	v_rcp_f32_e32 v242, v242
	v_rcp_f32_e32 v243, v243
	v_rcp_f32_e32 v244, v244
	v_rcp_f32_e32 v245, v245
	v_rcp_f32_e32 v246, v246
	v_rcp_f32_e32 v247, v247
	v_pk_mul_f32 v[88:89], v[88:89], v[240:241]
	v_pk_mul_f32 v[90:91], v[90:91], v[242:243]
	v_pk_mul_f32 v[80:81], v[80:81], v[244:245]
	v_pk_mul_f32 v[82:83], v[82:83], v[246:247]
	v_cvt_pk_bf16_f32 v232, v88, v89
	v_cvt_pk_bf16_f32 v233, v90, v91
	v_cvt_pk_bf16_f32 v234, v80, v81
	v_cvt_pk_bf16_f32 v235, v82, v83
	flat_store_dwordx4 v[236:237], v[232:235]
	v_or_b32_e32 v238, 48, v154
	v_mad_i64_i32 v[236:237], s[20:21], v238, s43, v[146:147]
	v_pk_mul_f32 v[240:241], v[76:77], v[228:229]
	v_pk_mul_f32 v[242:243], v[78:79], v[228:229]
	v_pk_mul_f32 v[244:245], v[68:69], v[228:229]
	v_pk_mul_f32 v[246:247], v[70:71], v[228:229]
	v_lshl_add_u64 v[236:237], v[236:237], 0, v[144:145]
	v_exp_f32_e32 v240, v240
	v_exp_f32_e32 v241, v241
	v_exp_f32_e32 v242, v242
	v_exp_f32_e32 v243, v243
	v_exp_f32_e32 v244, v244
	v_exp_f32_e32 v245, v245
	v_exp_f32_e32 v246, v246
	v_exp_f32_e32 v247, v247
	v_pk_mul_f32 v[72:73], v[76:77], v[72:73]
	v_pk_mul_f32 v[74:75], v[78:79], v[74:75]
	v_pk_mul_f32 v[64:65], v[68:69], v[64:65]
	v_pk_mul_f32 v[66:67], v[70:71], v[66:67]
	v_pk_add_f32 v[240:241], v[240:241], v[230:231]
	v_pk_add_f32 v[242:243], v[242:243], v[230:231]
	v_pk_add_f32 v[244:245], v[244:245], v[230:231]
; __device__ __forceinline__ unsigned cvt_pk_bf16(float lo, float hi) { unsigned r; asm volatile("v_cvt_pk_bf16_f32 %0, %1, %2" : "=v"(r) : "v"(lo), "v"(hi)); return r; }
; __device__ __forceinline__ float silu_mul(float g, float u) { return g * u * __builtin_amdgcn_rcpf(1.0f + __builtin_amdgcn_exp2f(-1.4426950408889634f * g)); }
; #define PG8_BAR __builtin_amdgcn_s_barrier()
;     __device__ __forceinline__ void operator()(const f32x4 (&acc)[2][2][4][2], const Unit& u, int wr, int wc, int fr, int fq) const {
;     ...
;         for (int ai = 0; ai < 2; ++ai)
; #pragma unroll
;             for (int m = 0; m < 4; ++m) { bf16_t* rowp = O + (size_t)(row0 + ai * HALF + m * 16) * ldc + col0;
;                 const f32x4 g0 = acc[ai][0][m][0], g1 = acc[ai][0][m][1], u0 = acc[ai][1][m][0], u1 = acc[ai][1][m][1];
;                 u32x4 w; w.x = cvt_pk_bf16(silu_mul(g0[0], u0[0]), silu_mul(g0[1], u0[1])); w.y = cvt_pk_bf16(silu_mul(g0[2], u0[2]), silu_mul(g0[3], u0[3]));
;                 w.z = cvt_pk_bf16(silu_mul(g1[0], u1[0]), silu_mul(g1[1], u1[1])); w.w = cvt_pk_bf16(silu_mul(g1[2], u1[2]), silu_mul(g1[3], u1[3]));
;                 *(u32x4*)rowp = w; }
; template <class Epi, class Sched, bool ALIGN_EPI = false, bool SP2 = false>
; __device__ __forceinline__ void gemm_phase(PG8_LAS unsigned char* lds, const Gemm g, const Sched& S, const Epi& E) {
;     ...
;         if constexpr (!Epi::AFTER_DRAIN) { E(acc, cur, wr, wc, fr, fq); S.done(cur); }
;         if (!has_next) break;
; #pragma unroll
;         for (int a = 0; a < 2; ++a)
; #pragma unroll
;             for (int b = 0; b < 2; ++b)
; #pragma unroll
;                 for (int m = 0; m < 4; ++m)
; #pragma unroll
;                     for (int n = 0; n < 2; ++n) acc[a][b][m][n] = (f32x4){0.f, 0.f, 0.f, 0.f};
;         cur = nxt; cA = nA; cB = nB; ++ui;
;         if constexpr (ALIGN_EPI) { if (wr == 1) PG8_BAR; }
	v_pk_add_f32 v[246:247], v[246:247], v[230:231]
	v_rcp_f32_e32 v240, v240
	v_rcp_f32_e32 v241, v241
	v_rcp_f32_e32 v242, v242
	v_rcp_f32_e32 v243, v243
	v_rcp_f32_e32 v244, v244
	v_rcp_f32_e32 v245, v245
	v_rcp_f32_e32 v246, v246
	v_rcp_f32_e32 v247, v247
	v_pk_mul_f32 v[72:73], v[72:73], v[240:241]
	v_pk_mul_f32 v[74:75], v[74:75], v[242:243]
	v_pk_mul_f32 v[64:65], v[64:65], v[244:245]
	v_pk_mul_f32 v[66:67], v[66:67], v[246:247]
	v_cvt_pk_bf16_f32 v232, v72, v73
	v_cvt_pk_bf16_f32 v233, v74, v75
	v_cvt_pk_bf16_f32 v234, v64, v65
	v_cvt_pk_bf16_f32 v235, v66, v67
	flat_store_dwordx4 v[236:237], v[232:235]
	v_add_u32_e32 v238, 0x80, v154
	v_mad_i64_i32 v[236:237], s[20:21], v238, s43, v[146:147]
	v_pk_mul_f32 v[240:241], v[60:61], v[228:229]
	v_pk_mul_f32 v[242:243], v[62:63], v[228:229]
	v_pk_mul_f32 v[244:245], v[52:53], v[228:229]
	v_pk_mul_f32 v[246:247], v[54:55], v[228:229]
	v_lshl_add_u64 v[236:237], v[236:237], 0, v[144:145]
	v_exp_f32_e32 v240, v240
	v_exp_f32_e32 v241, v241
	v_exp_f32_e32 v242, v242
	v_exp_f32_e32 v243, v243
	v_exp_f32_e32 v244, v244
	v_exp_f32_e32 v245, v245
	v_exp_f32_e32 v246, v246
	v_exp_f32_e32 v247, v247
	v_pk_mul_f32 v[56:57], v[60:61], v[56:57]
	v_pk_mul_f32 v[58:59], v[62:63], v[58:59]
	v_pk_mul_f32 v[48:49], v[52:53], v[48:49]
	v_pk_mul_f32 v[50:51], v[54:55], v[50:51]
	v_pk_add_f32 v[240:241], v[240:241], v[230:231]
	v_pk_add_f32 v[242:243], v[242:243], v[230:231]
	v_pk_add_f32 v[244:245], v[244:245], v[230:231]
	v_pk_add_f32 v[246:247], v[246:247], v[230:231]
	v_rcp_f32_e32 v240, v240
	v_rcp_f32_e32 v241, v241
	v_rcp_f32_e32 v242, v242
	v_rcp_f32_e32 v243, v243
	v_rcp_f32_e32 v244, v244
	v_rcp_f32_e32 v245, v245
	v_rcp_f32_e32 v246, v246
	v_rcp_f32_e32 v247, v247
	v_pk_mul_f32 v[56:57], v[56:57], v[240:241]
	v_pk_mul_f32 v[58:59], v[58:59], v[242:243]
	v_pk_mul_f32 v[48:49], v[48:49], v[244:245]
	v_pk_mul_f32 v[50:51], v[50:51], v[246:247]
	v_cvt_pk_bf16_f32 v232, v56, v57
	v_cvt_pk_bf16_f32 v233, v58, v59
	v_cvt_pk_bf16_f32 v234, v48, v49
	v_cvt_pk_bf16_f32 v235, v50, v51
	flat_store_dwordx4 v[236:237], v[232:235]
	v_add_u32_e32 v238, 0x90, v154
	v_mad_i64_i32 v[236:237], s[20:21], v238, s43, v[146:147]
	v_pk_mul_f32 v[240:241], v[44:45], v[228:229]
	v_pk_mul_f32 v[242:243], v[46:47], v[228:229]
	v_pk_mul_f32 v[244:245], v[36:37], v[228:229]
	v_pk_mul_f32 v[246:247], v[38:39], v[228:229]
	v_lshl_add_u64 v[236:237], v[236:237], 0, v[144:145]
	v_exp_f32_e32 v240, v240
	v_exp_f32_e32 v241, v241
	v_exp_f32_e32 v242, v242
	v_exp_f32_e32 v243, v243
	v_exp_f32_e32 v244, v244
	v_exp_f32_e32 v245, v245
	v_exp_f32_e32 v246, v246
	v_exp_f32_e32 v247, v247
	v_pk_mul_f32 v[40:41], v[44:45], v[40:41]
	v_pk_mul_f32 v[42:43], v[46:47], v[42:43]
	v_pk_mul_f32 v[32:33], v[36:37], v[32:33]
	v_pk_mul_f32 v[34:35], v[38:39], v[34:35]
	v_pk_add_f32 v[240:241], v[240:241], v[230:231]
	v_pk_add_f32 v[242:243], v[242:243], v[230:231]
	v_pk_add_f32 v[244:245], v[244:245], v[230:231]
	v_pk_add_f32 v[246:247], v[246:247], v[230:231]
	v_rcp_f32_e32 v240, v240
	v_rcp_f32_e32 v241, v241
	v_rcp_f32_e32 v242, v242
	v_rcp_f32_e32 v243, v243
	v_rcp_f32_e32 v244, v244
	v_rcp_f32_e32 v245, v245
	v_rcp_f32_e32 v246, v246
	v_rcp_f32_e32 v247, v247
	v_pk_mul_f32 v[40:41], v[40:41], v[240:241]
	v_pk_mul_f32 v[42:43], v[42:43], v[242:243]
	v_pk_mul_f32 v[32:33], v[32:33], v[244:245]
	v_pk_mul_f32 v[34:35], v[34:35], v[246:247]
	v_cvt_pk_bf16_f32 v232, v40, v41
	v_cvt_pk_bf16_f32 v233, v42, v43
	v_cvt_pk_bf16_f32 v234, v32, v33
	v_cvt_pk_bf16_f32 v235, v34, v35
	flat_store_dwordx4 v[236:237], v[232:235]
	v_add_u32_e32 v238, 0xa0, v154
	v_mad_i64_i32 v[236:237], s[20:21], v238, s43, v[146:147]
	v_pk_mul_f32 v[240:241], v[28:29], v[228:229]
	v_pk_mul_f32 v[242:243], v[30:31], v[228:229]
	v_pk_mul_f32 v[244:245], v[20:21], v[228:229]
	v_pk_mul_f32 v[246:247], v[22:23], v[228:229]
	v_lshl_add_u64 v[236:237], v[236:237], 0, v[144:145]
	v_exp_f32_e32 v240, v240
	v_exp_f32_e32 v241, v241
	v_exp_f32_e32 v242, v242
	v_exp_f32_e32 v243, v243
	v_exp_f32_e32 v244, v244
	v_exp_f32_e32 v245, v245
	v_exp_f32_e32 v246, v246
	v_exp_f32_e32 v247, v247
	v_pk_mul_f32 v[24:25], v[28:29], v[24:25]
	v_pk_mul_f32 v[26:27], v[30:31], v[26:27]
	v_pk_mul_f32 v[16:17], v[20:21], v[16:17]
	v_pk_mul_f32 v[18:19], v[22:23], v[18:19]
	v_pk_add_f32 v[240:241], v[240:241], v[230:231]
	v_pk_add_f32 v[242:243], v[242:243], v[230:231]
	v_pk_add_f32 v[244:245], v[244:245], v[230:231]
	v_pk_add_f32 v[246:247], v[246:247], v[230:231]
	v_rcp_f32_e32 v240, v240
	v_rcp_f32_e32 v241, v241
	v_rcp_f32_e32 v242, v242
	v_rcp_f32_e32 v243, v243
	v_rcp_f32_e32 v244, v244
	v_rcp_f32_e32 v245, v245
	v_rcp_f32_e32 v246, v246
	v_rcp_f32_e32 v247, v247
	v_pk_mul_f32 v[24:25], v[24:25], v[240:241]
	v_pk_mul_f32 v[26:27], v[26:27], v[242:243]
	v_pk_mul_f32 v[16:17], v[16:17], v[244:245]
	v_pk_mul_f32 v[18:19], v[18:19], v[246:247]
	v_cvt_pk_bf16_f32 v232, v24, v25
	v_cvt_pk_bf16_f32 v233, v26, v27
	v_cvt_pk_bf16_f32 v234, v16, v17
	v_cvt_pk_bf16_f32 v235, v18, v19
	flat_store_dwordx4 v[236:237], v[232:235]
	v_add_u32_e32 v238, 0xb0, v154
	v_mad_i64_i32 v[236:237], s[20:21], v238, s43, v[146:147]
	v_pk_mul_f32 v[240:241], v[12:13], v[228:229]
	v_pk_mul_f32 v[242:243], v[14:15], v[228:229]
	v_pk_mul_f32 v[244:245], v[4:5], v[228:229]
	v_pk_mul_f32 v[246:247], v[6:7], v[228:229]
	v_lshl_add_u64 v[236:237], v[236:237], 0, v[144:145]
	v_exp_f32_e32 v240, v240
	v_exp_f32_e32 v241, v241
	v_exp_f32_e32 v242, v242
	v_exp_f32_e32 v243, v243
	v_exp_f32_e32 v244, v244
	v_exp_f32_e32 v245, v245
	v_exp_f32_e32 v246, v246
	v_exp_f32_e32 v247, v247
	v_pk_mul_f32 v[8:9], v[12:13], v[8:9]
	v_pk_mul_f32 v[10:11], v[14:15], v[10:11]
	v_pk_mul_f32 v[0:1], v[4:5], v[0:1]
	v_pk_mul_f32 v[2:3], v[6:7], v[2:3]
	v_pk_add_f32 v[240:241], v[240:241], v[230:231]
	v_pk_add_f32 v[242:243], v[242:243], v[230:231]
	v_pk_add_f32 v[244:245], v[244:245], v[230:231]
	v_pk_add_f32 v[246:247], v[246:247], v[230:231]
	v_rcp_f32_e32 v240, v240
	v_rcp_f32_e32 v241, v241
	v_rcp_f32_e32 v242, v242
	v_rcp_f32_e32 v243, v243
	v_rcp_f32_e32 v244, v244
	v_rcp_f32_e32 v245, v245
	v_rcp_f32_e32 v246, v246
	v_rcp_f32_e32 v247, v247
	v_pk_mul_f32 v[8:9], v[8:9], v[240:241]
	v_pk_mul_f32 v[10:11], v[10:11], v[242:243]
	v_pk_mul_f32 v[0:1], v[0:1], v[244:245]
	v_pk_mul_f32 v[2:3], v[2:3], v[246:247]
	v_cvt_pk_bf16_f32 v232, v8, v9
	v_cvt_pk_bf16_f32 v233, v10, v11
	v_cvt_pk_bf16_f32 v234, v0, v1
	v_cvt_pk_bf16_f32 v235, v2, v3
	flat_store_dwordx4 v[236:237], v[232:235]
	s_andn2_b64 vcc, exec, s[2:3]
	s_mov_b64 s[2:3], -1
	s_cbranch_vccnz .LBB0_116
	s_andn2_b64 vcc, exec, s[0:1]
	s_cbranch_vccnz .LBB0_115
	s_barrier
	s_branch .LBB0_115

; __device__ __forceinline__ unsigned cvt_pk_bf16(float lo, float hi) { unsigned r; asm volatile("v_cvt_pk_bf16_f32 %0, %1, %2" : "=v"(r) : "v"(lo), "v"(hi)); return r; }
; __device__ __forceinline__ float silu_mul(float g, float u) { return g * u * __builtin_amdgcn_rcpf(1.0f + __builtin_amdgcn_exp2f(-1.4426950408889634f * g)); }
;     __device__ __forceinline__ void operator()(const f32x4 (&acc)[2][2][4][2], const Unit& u, int wr, int wc, int fr, int fq) const {
;         const int row0 = u.pm * BM + wr * 64 + fr, col0 = u.pn * HALF + wc * 32 + 8 * fq;
; #pragma unroll
;         for (int ai = 0; ai < 2; ++ai)
; #pragma unroll
;             for (int m = 0; m < 4; ++m) { bf16_t* rowp = O + (size_t)(row0 + ai * HALF + m * 16) * ldc + col0;
;                 const f32x4 g0 = acc[ai][0][m][0], g1 = acc[ai][0][m][1], u0 = acc[ai][1][m][0], u1 = acc[ai][1][m][1];
;                 u32x4 w; w.x = cvt_pk_bf16(silu_mul(g0[0], u0[0]), silu_mul(g0[1], u0[1])); w.y = cvt_pk_bf16(silu_mul(g0[2], u0[2]), silu_mul(g0[3], u0[3]));
;                 w.z = cvt_pk_bf16(silu_mul(g1[0], u1[0]), silu_mul(g1[1], u1[1])); w.w = cvt_pk_bf16(silu_mul(g1[2], u1[2]), silu_mul(g1[3], u1[3]));
;                 *(u32x4*)rowp = w; }
.LBB0_1020:
	v_mov_b32_e32 v228, 0xbfb8aa3b
	v_mov_b32_e32 v229, 0xbfb8aa3b
	v_mov_b32_e32 v230, 1.0
	v_mov_b32_e32 v231, 1.0
	v_lshl_or_b32 v144, s45, 7, v150
	v_lshl_add_u32 v154, s20, 8, v148
	v_ashrrev_i32_e32 v145, 31, v144
	v_mov_b64_e32 v[146:147], s[6:7]
	v_lshlrev_b64 v[144:145], 1, v[144:145]
	v_mad_i64_i32 v[236:237], s[22:23], v154, s44, v[146:147]
	v_pk_mul_f32 v[240:241], v[124:125], v[228:229]
	v_pk_mul_f32 v[242:243], v[126:127], v[228:229]
	v_pk_mul_f32 v[244:245], v[116:117], v[228:229]
	v_pk_mul_f32 v[246:247], v[118:119], v[228:229]
	v_lshl_add_u64 v[236:237], v[236:237], 0, v[144:145]
	v_exp_f32_e32 v240, v240
	v_exp_f32_e32 v241, v241
	v_exp_f32_e32 v242, v242
	v_exp_f32_e32 v243, v243
	v_exp_f32_e32 v244, v244
	v_exp_f32_e32 v245, v245
	v_exp_f32_e32 v246, v246
	v_exp_f32_e32 v247, v247
	v_pk_mul_f32 v[120:121], v[124:125], v[120:121]
	v_pk_mul_f32 v[122:123], v[126:127], v[122:123]
	v_pk_mul_f32 v[112:113], v[116:117], v[112:113]
	v_pk_mul_f32 v[114:115], v[118:119], v[114:115]
	v_pk_add_f32 v[240:241], v[240:241], v[230:231]
	v_pk_add_f32 v[242:243], v[242:243], v[230:231]
	v_pk_add_f32 v[244:245], v[244:245], v[230:231]
	v_pk_add_f32 v[246:247], v[246:247], v[230:231]
	v_rcp_f32_e32 v240, v240
	v_rcp_f32_e32 v241, v241
	v_rcp_f32_e32 v242, v242
	v_rcp_f32_e32 v243, v243
	v_rcp_f32_e32 v244, v244
	v_rcp_f32_e32 v245, v245
	v_rcp_f32_e32 v246, v246
	v_rcp_f32_e32 v247, v247
	v_pk_mul_f32 v[120:121], v[120:121], v[240:241]
	v_pk_mul_f32 v[122:123], v[122:123], v[242:243]
	v_pk_mul_f32 v[112:113], v[112:113], v[244:245]
	v_pk_mul_f32 v[114:115], v[114:115], v[246:247]
	v_cvt_pk_bf16_f32 v232, v120, v121
	v_cvt_pk_bf16_f32 v233, v122, v123
	v_cvt_pk_bf16_f32 v234, v112, v113
	v_cvt_pk_bf16_f32 v235, v114, v115
	flat_store_dwordx4 v[236:237], v[232:235]
	v_or_b32_e32 v238, 16, v154
	v_mad_i64_i32 v[236:237], s[22:23], v238, s44, v[146:147]
	v_pk_mul_f32 v[240:241], v[108:109], v[228:229]
	v_pk_mul_f32 v[242:243], v[110:111], v[228:229]
	v_pk_mul_f32 v[244:245], v[100:101], v[228:229]
	v_pk_mul_f32 v[246:247], v[102:103], v[228:229]
	v_lshl_add_u64 v[236:237], v[236:237], 0, v[144:145]
	v_exp_f32_e32 v240, v240
	v_exp_f32_e32 v241, v241
	v_exp_f32_e32 v242, v242
	v_exp_f32_e32 v243, v243
	v_exp_f32_e32 v244, v244
	v_exp_f32_e32 v245, v245
	v_exp_f32_e32 v246, v246
	v_exp_f32_e32 v247, v247
	v_pk_mul_f32 v[104:105], v[108:109], v[104:105]
	v_pk_mul_f32 v[106:107], v[110:111], v[106:107]
	v_pk_mul_f32 v[96:97], v[100:101], v[96:97]
	v_pk_mul_f32 v[98:99], v[102:103], v[98:99]
	v_pk_add_f32 v[240:241], v[240:241], v[230:231]
	v_pk_add_f32 v[242:243], v[242:243], v[230:231]
	v_pk_add_f32 v[244:245], v[244:245], v[230:231]
	v_pk_add_f32 v[246:247], v[246:247], v[230:231]
	v_rcp_f32_e32 v240, v240
	v_rcp_f32_e32 v241, v241
	v_rcp_f32_e32 v242, v242
	v_rcp_f32_e32 v243, v243
	v_rcp_f32_e32 v244, v244
	v_rcp_f32_e32 v245, v245
	v_rcp_f32_e32 v246, v246
	v_rcp_f32_e32 v247, v247
	v_pk_mul_f32 v[104:105], v[104:105], v[240:241]
	v_pk_mul_f32 v[106:107], v[106:107], v[242:243]
	v_pk_mul_f32 v[96:97], v[96:97], v[244:245]
	v_pk_mul_f32 v[98:99], v[98:99], v[246:247]
	v_cvt_pk_bf16_f32 v232, v104, v105
	v_cvt_pk_bf16_f32 v233, v106, v107
	v_cvt_pk_bf16_f32 v234, v96, v97
	v_cvt_pk_bf16_f32 v235, v98, v99
	flat_store_dwordx4 v[236:237], v[232:235]
	v_or_b32_e32 v238, 32, v154
	v_mad_i64_i32 v[236:237], s[22:23], v238, s44, v[146:147]
	v_pk_mul_f32 v[240:241], v[92:93], v[228:229]
	v_pk_mul_f32 v[242:243], v[94:95], v[228:229]
	v_pk_mul_f32 v[244:245], v[84:85], v[228:229]
	v_pk_mul_f32 v[246:247], v[86:87], v[228:229]
	v_lshl_add_u64 v[236:237], v[236:237], 0, v[144:145]
	v_exp_f32_e32 v240, v240
	v_exp_f32_e32 v241, v241
	v_exp_f32_e32 v242, v242
	v_exp_f32_e32 v243, v243
	v_exp_f32_e32 v244, v244
	v_exp_f32_e32 v245, v245
	v_exp_f32_e32 v246, v246
	v_exp_f32_e32 v247, v247
	v_pk_mul_f32 v[88:89], v[92:93], v[88:89]
	v_pk_mul_f32 v[90:91], v[94:95], v[90:91]
	v_pk_mul_f32 v[80:81], v[84:85], v[80:81]
	v_pk_mul_f32 v[82:83], v[86:87], v[82:83]
	v_pk_add_f32 v[240:241], v[240:241], v[230:231]
	v_pk_add_f32 v[242:243], v[242:243], v[230:231]
	v_pk_add_f32 v[244:245], v[244:245], v[230:231]
	v_pk_add_f32 v[246:247], v[246:247], v[230:231]
	v_rcp_f32_e32 v240, v240
	v_rcp_f32_e32 v241, v241
	v_rcp_f32_e32 v242, v242
	v_rcp_f32_e32 v243, v243
	v_rcp_f32_e32 v244, v244
	v_rcp_f32_e32 v245, v245
	v_rcp_f32_e32 v246, v246
	v_rcp_f32_e32 v247, v247
	v_pk_mul_f32 v[88:89], v[88:89], v[240:241]
	v_pk_mul_f32 v[90:91], v[90:91], v[242:243]
	v_pk_mul_f32 v[80:81], v[80:81], v[244:245]
	v_pk_mul_f32 v[82:83], v[82:83], v[246:247]
	v_cvt_pk_bf16_f32 v232, v88, v89
	v_cvt_pk_bf16_f32 v233, v90, v91
	v_cvt_pk_bf16_f32 v234, v80, v81
	v_cvt_pk_bf16_f32 v235, v82, v83
	flat_store_dwordx4 v[236:237], v[232:235]
	v_or_b32_e32 v238, 48, v154
	v_mad_i64_i32 v[236:237], s[22:23], v238, s44, v[146:147]
	v_pk_mul_f32 v[240:241], v[76:77], v[228:229]
	v_pk_mul_f32 v[242:243], v[78:79], v[228:229]
	v_pk_mul_f32 v[244:245], v[68:69], v[228:229]
	v_pk_mul_f32 v[246:247], v[70:71], v[228:229]
	v_lshl_add_u64 v[236:237], v[236:237], 0, v[144:145]
	v_exp_f32_e32 v240, v240
	v_exp_f32_e32 v241, v241
	v_exp_f32_e32 v242, v242
	v_exp_f32_e32 v243, v243
	v_exp_f32_e32 v244, v244
	v_exp_f32_e32 v245, v245
	v_exp_f32_e32 v246, v246
	v_exp_f32_e32 v247, v247
	v_pk_mul_f32 v[72:73], v[76:77], v[72:73]
	v_pk_mul_f32 v[74:75], v[78:79], v[74:75]
	v_pk_mul_f32 v[64:65], v[68:69], v[64:65]
	v_pk_mul_f32 v[66:67], v[70:71], v[66:67]
	v_pk_add_f32 v[240:241], v[240:241], v[230:231]
	v_pk_add_f32 v[242:243], v[242:243], v[230:231]
	v_pk_add_f32 v[244:245], v[244:245], v[230:231]
; __device__ __forceinline__ unsigned cvt_pk_bf16(float lo, float hi) { unsigned r; asm volatile("v_cvt_pk_bf16_f32 %0, %1, %2" : "=v"(r) : "v"(lo), "v"(hi)); return r; }
; __device__ __forceinline__ float silu_mul(float g, float u) { return g * u * __builtin_amdgcn_rcpf(1.0f + __builtin_amdgcn_exp2f(-1.4426950408889634f * g)); }
;     __device__ __forceinline__ void operator()(const f32x4 (&acc)[2][2][4][2], const Unit& u, int wr, int wc, int fr, int fq) const {
;         const int row0 = u.pm * BM + wr * 64 + fr, col0 = u.pn * HALF + wc * 32 + 8 * fq;
; #pragma unroll
;         for (int ai = 0; ai < 2; ++ai)
; #pragma unroll
;             for (int m = 0; m < 4; ++m) { bf16_t* rowp = O + (size_t)(row0 + ai * HALF + m * 16) * ldc + col0;
;                 const f32x4 g0 = acc[ai][0][m][0], g1 = acc[ai][0][m][1], u0 = acc[ai][1][m][0], u1 = acc[ai][1][m][1];
;                 u32x4 w; w.x = cvt_pk_bf16(silu_mul(g0[0], u0[0]), silu_mul(g0[1], u0[1])); w.y = cvt_pk_bf16(silu_mul(g0[2], u0[2]), silu_mul(g0[3], u0[3]));
;                 w.z = cvt_pk_bf16(silu_mul(g1[0], u1[0]), silu_mul(g1[1], u1[1])); w.w = cvt_pk_bf16(silu_mul(g1[2], u1[2]), silu_mul(g1[3], u1[3]));
;                 *(u32x4*)rowp = w; }
	v_pk_add_f32 v[246:247], v[246:247], v[230:231]
	v_rcp_f32_e32 v240, v240
	v_rcp_f32_e32 v241, v241
	v_rcp_f32_e32 v242, v242
	v_rcp_f32_e32 v243, v243
	v_rcp_f32_e32 v244, v244
	v_rcp_f32_e32 v245, v245
	v_rcp_f32_e32 v246, v246
	v_rcp_f32_e32 v247, v247
	v_pk_mul_f32 v[72:73], v[72:73], v[240:241]
	v_pk_mul_f32 v[74:75], v[74:75], v[242:243]
	v_pk_mul_f32 v[64:65], v[64:65], v[244:245]
	v_pk_mul_f32 v[66:67], v[66:67], v[246:247]
	v_cvt_pk_bf16_f32 v232, v72, v73
	v_cvt_pk_bf16_f32 v233, v74, v75
	v_cvt_pk_bf16_f32 v234, v64, v65
	v_cvt_pk_bf16_f32 v235, v66, v67
	flat_store_dwordx4 v[236:237], v[232:235]
	v_add_u32_e32 v238, 0x80, v154
	v_mad_i64_i32 v[236:237], s[22:23], v238, s44, v[146:147]
	v_pk_mul_f32 v[240:241], v[60:61], v[228:229]
	v_pk_mul_f32 v[242:243], v[62:63], v[228:229]
	v_pk_mul_f32 v[244:245], v[52:53], v[228:229]
	v_pk_mul_f32 v[246:247], v[54:55], v[228:229]
	v_lshl_add_u64 v[236:237], v[236:237], 0, v[144:145]
	v_exp_f32_e32 v240, v240
	v_exp_f32_e32 v241, v241
	v_exp_f32_e32 v242, v242
	v_exp_f32_e32 v243, v243
	v_exp_f32_e32 v244, v244
	v_exp_f32_e32 v245, v245
	v_exp_f32_e32 v246, v246
	v_exp_f32_e32 v247, v247
	v_pk_mul_f32 v[56:57], v[60:61], v[56:57]
	v_pk_mul_f32 v[58:59], v[62:63], v[58:59]
	v_pk_mul_f32 v[48:49], v[52:53], v[48:49]
	v_pk_mul_f32 v[50:51], v[54:55], v[50:51]
	v_pk_add_f32 v[240:241], v[240:241], v[230:231]
	v_pk_add_f32 v[242:243], v[242:243], v[230:231]
	v_pk_add_f32 v[244:245], v[244:245], v[230:231]
	v_pk_add_f32 v[246:247], v[246:247], v[230:231]
	v_rcp_f32_e32 v240, v240
	v_rcp_f32_e32 v241, v241
	v_rcp_f32_e32 v242, v242
	v_rcp_f32_e32 v243, v243
	v_rcp_f32_e32 v244, v244
	v_rcp_f32_e32 v245, v245
	v_rcp_f32_e32 v246, v246
	v_rcp_f32_e32 v247, v247
	v_pk_mul_f32 v[56:57], v[56:57], v[240:241]
	v_pk_mul_f32 v[58:59], v[58:59], v[242:243]
	v_pk_mul_f32 v[48:49], v[48:49], v[244:245]
	v_pk_mul_f32 v[50:51], v[50:51], v[246:247]
	v_cvt_pk_bf16_f32 v232, v56, v57
	v_cvt_pk_bf16_f32 v233, v58, v59
	v_cvt_pk_bf16_f32 v234, v48, v49
	v_cvt_pk_bf16_f32 v235, v50, v51
	flat_store_dwordx4 v[236:237], v[232:235]
	v_add_u32_e32 v238, 0x90, v154
	v_mad_i64_i32 v[236:237], s[22:23], v238, s44, v[146:147]
	v_pk_mul_f32 v[240:241], v[44:45], v[228:229]
	v_pk_mul_f32 v[242:243], v[46:47], v[228:229]
	v_pk_mul_f32 v[244:245], v[36:37], v[228:229]
	v_pk_mul_f32 v[246:247], v[38:39], v[228:229]
	v_lshl_add_u64 v[236:237], v[236:237], 0, v[144:145]
	v_exp_f32_e32 v240, v240
	v_exp_f32_e32 v241, v241
	v_exp_f32_e32 v242, v242
	v_exp_f32_e32 v243, v243
	v_exp_f32_e32 v244, v244
	v_exp_f32_e32 v245, v245
	v_exp_f32_e32 v246, v246
	v_exp_f32_e32 v247, v247
	v_pk_mul_f32 v[40:41], v[44:45], v[40:41]
	v_pk_mul_f32 v[42:43], v[46:47], v[42:43]
	v_pk_mul_f32 v[32:33], v[36:37], v[32:33]
	v_pk_mul_f32 v[34:35], v[38:39], v[34:35]
	v_pk_add_f32 v[240:241], v[240:241], v[230:231]
	v_pk_add_f32 v[242:243], v[242:243], v[230:231]
	v_pk_add_f32 v[244:245], v[244:245], v[230:231]
	v_pk_add_f32 v[246:247], v[246:247], v[230:231]
	v_rcp_f32_e32 v240, v240
	v_rcp_f32_e32 v241, v241
	v_rcp_f32_e32 v242, v242
	v_rcp_f32_e32 v243, v243
	v_rcp_f32_e32 v244, v244
	v_rcp_f32_e32 v245, v245
	v_rcp_f32_e32 v246, v246
	v_rcp_f32_e32 v247, v247
	v_pk_mul_f32 v[40:41], v[40:41], v[240:241]
	v_pk_mul_f32 v[42:43], v[42:43], v[242:243]
	v_pk_mul_f32 v[32:33], v[32:33], v[244:245]
	v_pk_mul_f32 v[34:35], v[34:35], v[246:247]
	v_cvt_pk_bf16_f32 v232, v40, v41
	v_cvt_pk_bf16_f32 v233, v42, v43
	v_cvt_pk_bf16_f32 v234, v32, v33
	v_cvt_pk_bf16_f32 v235, v34, v35
	flat_store_dwordx4 v[236:237], v[232:235]
	v_add_u32_e32 v238, 0xa0, v154
	v_mad_i64_i32 v[236:237], s[22:23], v238, s44, v[146:147]
	v_pk_mul_f32 v[240:241], v[28:29], v[228:229]
	v_pk_mul_f32 v[242:243], v[30:31], v[228:229]
	v_pk_mul_f32 v[244:245], v[20:21], v[228:229]
	v_pk_mul_f32 v[246:247], v[22:23], v[228:229]
	v_lshl_add_u64 v[236:237], v[236:237], 0, v[144:145]
	v_exp_f32_e32 v240, v240
	v_exp_f32_e32 v241, v241
	v_exp_f32_e32 v242, v242
	v_exp_f32_e32 v243, v243
	v_exp_f32_e32 v244, v244
	v_exp_f32_e32 v245, v245
	v_exp_f32_e32 v246, v246
	v_exp_f32_e32 v247, v247
	v_pk_mul_f32 v[24:25], v[28:29], v[24:25]
	v_pk_mul_f32 v[26:27], v[30:31], v[26:27]
	v_pk_mul_f32 v[16:17], v[20:21], v[16:17]
	v_pk_mul_f32 v[18:19], v[22:23], v[18:19]
	v_pk_add_f32 v[240:241], v[240:241], v[230:231]
	v_pk_add_f32 v[242:243], v[242:243], v[230:231]
	v_pk_add_f32 v[244:245], v[244:245], v[230:231]
	v_pk_add_f32 v[246:247], v[246:247], v[230:231]
	v_rcp_f32_e32 v240, v240
	v_rcp_f32_e32 v241, v241
	v_rcp_f32_e32 v242, v242
	v_rcp_f32_e32 v243, v243
	v_rcp_f32_e32 v244, v244
	v_rcp_f32_e32 v245, v245
	v_rcp_f32_e32 v246, v246
	v_rcp_f32_e32 v247, v247
	v_pk_mul_f32 v[24:25], v[24:25], v[240:241]
	v_pk_mul_f32 v[26:27], v[26:27], v[242:243]
	v_pk_mul_f32 v[16:17], v[16:17], v[244:245]
	v_pk_mul_f32 v[18:19], v[18:19], v[246:247]
	v_cvt_pk_bf16_f32 v232, v24, v25
	v_cvt_pk_bf16_f32 v233, v26, v27
	v_cvt_pk_bf16_f32 v234, v16, v17
	v_cvt_pk_bf16_f32 v235, v18, v19
	flat_store_dwordx4 v[236:237], v[232:235]
	v_add_u32_e32 v238, 0xb0, v154
	v_mad_i64_i32 v[236:237], s[22:23], v238, s44, v[146:147]
	v_pk_mul_f32 v[240:241], v[12:13], v[228:229]
	v_pk_mul_f32 v[242:243], v[14:15], v[228:229]
	v_pk_mul_f32 v[244:245], v[4:5], v[228:229]
	v_pk_mul_f32 v[246:247], v[6:7], v[228:229]
	v_lshl_add_u64 v[236:237], v[236:237], 0, v[144:145]
	v_exp_f32_e32 v240, v240
	v_exp_f32_e32 v241, v241
	v_exp_f32_e32 v242, v242
	v_exp_f32_e32 v243, v243
	v_exp_f32_e32 v244, v244
	v_exp_f32_e32 v245, v245
	v_exp_f32_e32 v246, v246
	v_exp_f32_e32 v247, v247
	v_pk_mul_f32 v[8:9], v[12:13], v[8:9]
	v_pk_mul_f32 v[10:11], v[14:15], v[10:11]
	v_pk_mul_f32 v[0:1], v[4:5], v[0:1]
	v_pk_mul_f32 v[2:3], v[6:7], v[2:3]
	v_pk_add_f32 v[240:241], v[240:241], v[230:231]
	v_pk_add_f32 v[242:243], v[242:243], v[230:231]
	v_pk_add_f32 v[244:245], v[244:245], v[230:231]
	v_pk_add_f32 v[246:247], v[246:247], v[230:231]
	v_rcp_f32_e32 v240, v240
	v_rcp_f32_e32 v241, v241
	v_rcp_f32_e32 v242, v242
	v_rcp_f32_e32 v243, v243
	v_rcp_f32_e32 v244, v244
	v_rcp_f32_e32 v245, v245
	v_rcp_f32_e32 v246, v246
	v_rcp_f32_e32 v247, v247
	v_pk_mul_f32 v[8:9], v[8:9], v[240:241]
	v_pk_mul_f32 v[10:11], v[10:11], v[242:243]
	v_pk_mul_f32 v[0:1], v[0:1], v[244:245]
	v_pk_mul_f32 v[2:3], v[2:3], v[246:247]
	v_cvt_pk_bf16_f32 v232, v8, v9
	v_cvt_pk_bf16_f32 v233, v10, v11
	v_cvt_pk_bf16_f32 v234, v0, v1
	v_cvt_pk_bf16_f32 v235, v2, v3
	flat_store_dwordx4 v[236:237], v[232:235]
	s_andn2_b64 vcc, exec, s[4:5]
	s_mov_b64 s[4:5], -1
	s_cbranch_vccnz .LBB0_1009
	s_andn2_b64 vcc, exec, s[0:1]
	s_cbranch_vccnz .LBB0_1008
	s_barrier
	s_branch .LBB0_1008
